# v6 plus overhead trims in the attention loop: merged waitcnts per QK MFMA pair, cvt/swap groups reordered to avoid hazard nops, redundant add removed
# speedup vs baseline: 1.0049x; 1.0049x over previous
; #define SBAR() __builtin_amdgcn_sched_barrier(0)
; #define SLOAD(i, k0) do { sr_[i].a0 = *reinterpret_cast<const bf16x8*>(&KVh[(size_t)((k0) + sr) * NKV + c16 * 8]); sr_[i].a1 = *reinterpret_cast<const bf16x8*>(&KVh[(size_t)((k0) + 32 + sr) * NKV + c16 * 8]); \
;     sr_[i].rr = *reinterpret_cast<const bf16x8*>(&KR[(size_t)((k0) + rkey) * 32 + rch * 8]); } while (0)
; __device__ __forceinline__ void finishSM(f32x16& p0, f32x16& p1, float alpha, float& l_reg, bf16x8& pa0, bf16x8& pa1, bf16x8& pa2, bf16x8& pa3) {
; #pragma unroll
;     for (int r = 0; r < 16; ++r) p1[r] = __builtin_amdgcn_exp2f(p1[r]);
;     float ps;
;     { typedef float f32x2 __attribute__((ext_vector_type(2))); f32x2 s0 = {p0[0], p0[1]}, s1 = {p1[0], p1[1]};
; #pragma unroll
;       for (int r = 2; r < 16; r += 2) { s0 += (f32x2){p0[r], p0[r + 1]}; s1 += (f32x2){p1[r], p1[r + 1]}; }
;       s0 += s1; ps = s0.x + s0.y; }
;     { auto rr = __builtin_amdgcn_permlane32_swap(__float_as_uint(ps), __float_as_uint(ps), false, false);
;       ps = __uint_as_float(rr[0]) + __uint_as_float(rr[1]); }
;     l_reg = l_reg * alpha + ps;
;     ...
;     PK4(p0, 0, pa0); PK4(p0, 8, pa1); PK4(p1, 0, pa2); PK4(p1, 8, pa3);
;     ...
; }
; __device__ __forceinline__ void qkt(f32x16& p0, f32x16& p1, const char* Ks, const bf16x8* qr, int r32, int hi) {
;     p0 = f32x16{}; p1 = f32x16{};
; #pragma unroll
;     for (int d0 = 0; d0 < 6; ++d0) { const int cb = (d0 * 16 + hi * 8) * 2;
;         bf16x8 b0 = *reinterpret_cast<const bf16x8*>(Ks + KSWZ(r32, cb));
;         bf16x8 b1 = *reinterpret_cast<const bf16x8*>(Ks + KSWZ(32 + r32, cb));
;         p0 = __builtin_amdgcn_mfma_f32_32x32x16_bf16(b0, qr[d0], p0, 0, 0, 0);
;         p1 = __builtin_amdgcn_mfma_f32_32x32x16_bf16(b1, qr[d0], p1, 0, 0, 0); }
; __device__ __forceinline__ void attn_body(const bf16_t* __restrict__ Qb, const bf16_t* __restrict__ KVh, const bf16_t* __restrict__ KR, const float* __restrict__ ropeq,
;                                           bf16_t* __restrict__ Ob, int seq, char* lds, const int tid) {
;     ...
;         SBAR(); qkt(pB0, pB1, K_lds + bc * SHM_K, qr, r32, hi);
;         finishSM(pA0, pA1, alA, l_reg, pa0, pa1, pa2, pa3); SBAR();
;         SLOAD(SO, (j + 2) * KVBLK); SBAR();
;         pv_d0(o, vb0 + bp * (int)SHM_V, pa0, pa1, pa2, pa3); partialSM(pB0, pB1, m_reg, mnB, alB);
;         SWAIT(); SWRITE(bn, SE);
.Lattn_loop:
	s_mov_b32 s19, s6
	s_lshl_b32 s14, s18, 14
	s_lshl_b32 s22, s16, 14
	s_lshl_b32 s15, s19, 14
	s_add_u32 s61, s22, s58
	v_add_u32_e32 v254, s14, v188
	ds_read_b128 v[234:237], v254 offset:49152
	ds_read_b128 v[238:241], v254 offset:57344
	v_add_u32_e32 v254, s14, v189
	ds_read_b128 v[242:245], v254 offset:49152
	ds_read_b128 v[246:249], v254 offset:57344
	v_exp_f32_e32 v226, v124
	v_exp_f32_e32 v227, v125
	v_add_f32_e32 v250, v116, v114
	v_add_f32_e32 v251, v117, v115
	v_add_f32_e32 v250, v112, v250
	v_add_f32_e32 v251, v113, v251
	v_exp_f32_e32 v228, v122
	v_exp_f32_e32 v229, v123
	s_waitcnt lgkmcnt(2)
	v_mfma_f32_32x32x16_bf16 v[48:63], v[234:237], v[78:81], 0
	v_add_f32_e32 v250, v110, v250
	v_add_f32_e32 v251, v111, v251
	v_add_f32_e32 v250, v108, v250
	v_add_f32_e32 v251, v109, v251
	v_exp_f32_e32 v230, v120
	v_exp_f32_e32 v231, v121
	v_add_f32_e32 v250, v106, v250
	v_add_f32_e32 v251, v107, v251
	v_mfma_f32_32x32x16_bf16 v[32:47], v[238:241], v[78:81], 0
	v_add_u32_e32 v254, s14, v212
	ds_read_b128 v[234:237], v254 offset:49152
	ds_read_b128 v[238:241], v254 offset:57344
	v_add_f32_e32 v250, v102, v250
	v_add_f32_e32 v251, v103, v251
	v_exp_f32_e32 v232, v118
	v_exp_f32_e32 v233, v119
	v_add_f32_e32 v250, v104, v250
	v_add_f32_e32 v251, v105, v251
	v_cvt_pk_bf16_f32 v116, v116, v117
	s_waitcnt lgkmcnt(2)
	v_mfma_f32_32x32x16_bf16 v[48:63], v[242:245], v[74:77], v[48:63]
	v_cvt_pk_bf16_f32 v117, v114, v115
	v_cvt_pk_bf16_f32 v118, v112, v113
	v_cvt_pk_bf16_f32 v119, v110, v111
	v_cvt_pk_bf16_f32 v120, v108, v109
	v_cvt_pk_bf16_f32 v121, v106, v107
	v_mfma_f32_32x32x16_bf16 v[32:47], v[246:249], v[74:77], v[32:47]
	v_add_u32_e32 v254, s14, v213
	ds_read_b128 v[242:245], v254 offset:49152
	ds_read_b128 v[246:249], v254 offset:57344
	v_cvt_pk_bf16_f32 v122, v102, v103
	v_cvt_pk_bf16_f32 v123, v104, v105
	v_permlane32_swap_b32_e32 v116, v118
	v_permlane32_swap_b32_e32 v117, v119
	v_permlane32_swap_b32_e32 v120, v122
	s_waitcnt lgkmcnt(2)
	v_mfma_f32_32x32x16_bf16 v[48:63], v[234:237], v[70:73], v[48:63]
	v_permlane32_swap_b32_e32 v121, v123
	v_exp_f32_e32 v180, v180
	v_exp_f32_e32 v181, v181
	v_exp_f32_e32 v176, v176
	v_exp_f32_e32 v177, v177
	s_waitcnt vmcnt(0)
	s_xor_b32 s60, s60, 0x400
	v_mov_b32_e32 v255, s60
	v_cndmask_b32_e64 v255, 0, v255, s[0:1]
	v_add3_u32 v254, s15, v217, v255
	v_add_u32_e32 v255, v254, v218
	v_add_u32_e32 v254, v254, v219
	ds_write_b128 v255, v[90:93]
	ds_write_b128 v254, v[94:97]
	s_cmp_eq_u64 s[2:3], 0
	s_cbranch_scc1 .Lattn_swB
	v_add_u32_e32 v254, s15, v186
	ds_write_b128 v254, v[98:101] offset:49152
.Lattn_swB:
	v_mfma_f32_32x32x16_bf16 v[32:47], v[238:241], v[70:73], v[32:47]
	v_add_u32_e32 v254, s14, v214
	ds_read_b128 v[234:237], v254 offset:49152
	ds_read_b128 v[238:241], v254 offset:57344
	v_exp_f32_e32 v128, v128
	v_exp_f32_e32 v129, v129
	v_exp_f32_e32 v202, v126
	v_exp_f32_e32 v203, v127
	s_waitcnt lgkmcnt(4)
	v_mfma_f32_32x32x16_bf16 v[48:63], v[242:245], v[66:69], v[48:63]
	v_add_f32_e32 v174, v180, v176
	v_add_f32_e32 v175, v181, v177
	v_add_f32_e32 v174, v128, v174
	v_add_f32_e32 v175, v129, v175
	v_add_f32_e32 v174, v202, v174
	v_add_f32_e32 v175, v203, v175
	v_add_f32_e32 v174, v226, v174
	v_add_f32_e32 v175, v227, v175
	v_lshl_add_u64 v[106:107], s[28:29], 0, v[168:169]
	global_load_dwordx4 v[106:109], v[106:107], off
	v_lshl_add_u64 v[110:111], s[30:31], 0, v[168:169]
	global_load_dwordx4 v[110:113], v[110:111], off
	v_lshl_add_u64 v[102:103], s[26:27], 0, v[172:173]
	global_load_dwordx4 v[102:105], v[102:103], off
	v_mfma_f32_32x32x16_bf16 v[32:47], v[246:249], v[66:69], v[32:47]
	v_add_u32_e32 v254, s14, v215
	ds_read_b128 v[242:245], v254 offset:49152
	ds_read_b128 v[246:249], v254 offset:57344
	v_add_f32_e32 v174, v228, v174
	v_add_f32_e32 v175, v229, v175
	v_add_f32_e32 v174, v230, v174
	v_add_f32_e32 v175, v231, v175
	v_add_f32_e32 v174, v232, v174
	v_add_f32_e32 v175, v233, v175
	v_add_f32_e32 v250, v250, v174
	v_add_f32_e32 v251, v251, v175
	s_waitcnt lgkmcnt(2)
	v_mfma_f32_32x32x16_bf16 v[48:63], v[234:237], v[82:85], v[48:63]
	v_add_f32_e32 v174, v250, v251
	v_mov_b32_e32 v175, v174
	v_cvt_pk_bf16_f32 v124, v180, v181
	v_cvt_pk_bf16_f32 v125, v176, v177
	v_mfma_f32_32x32x16_bf16 v[32:47], v[238:241], v[82:85], v[32:47]
	v_add_u32_e32 v255, s61, v185
	ds_read_b64_tr_b16 v[234:235], v255 offset:0
	ds_read_b64_tr_b16 v[236:237], v255 offset:2048
	ds_read_b64_tr_b16 v[238:239], v255 offset:4096
	ds_read_b64_tr_b16 v[240:241], v255 offset:6144
	v_cvt_pk_bf16_f32 v126, v128, v129
	v_cvt_pk_bf16_f32 v127, v202, v203
	v_permlane32_swap_b32_e32 v174, v175
	v_cvt_pk_bf16_f32 v226, v226, v227
	s_waitcnt lgkmcnt(4)
	v_mfma_f32_32x32x16_bf16 v[48:63], v[242:245], v[86:89], v[48:63]
	v_cvt_pk_bf16_f32 v227, v228, v229
	v_cvt_pk_bf16_f32 v228, v230, v231
	v_cvt_pk_bf16_f32 v229, v232, v233
	v_permlane32_swap_b32_e32 v124, v126
	v_mfma_f32_32x32x16_bf16 v[32:47], v[246:249], v[86:89], v[32:47]
	ds_read_b64_tr_b16 v[242:243], v255 offset:8192
	ds_read_b64_tr_b16 v[244:245], v255 offset:10240
	ds_read_b64_tr_b16 v[246:247], v255 offset:12288
	ds_read_b64_tr_b16 v[248:249], v255 offset:14336
	v_permlane32_swap_b32_e32 v125, v127
	v_permlane32_swap_b32_e32 v226, v228
	v_permlane32_swap_b32_e32 v227, v229
	s_waitcnt lgkmcnt(8)
	s_cmp_eq_u64 s[2:3], 0
	s_cbranch_scc0 .Lattn_cb1
	s_barrier

; #define SBAR() __builtin_amdgcn_sched_barrier(0)
; #define SLOAD(i, k0) do { sr_[i].a0 = *reinterpret_cast<const bf16x8*>(&KVh[(size_t)((k0) + sr) * NKV + c16 * 8]); sr_[i].a1 = *reinterpret_cast<const bf16x8*>(&KVh[(size_t)((k0) + 32 + sr) * NKV + c16 * 8]); \
;     sr_[i].rr = *reinterpret_cast<const bf16x8*>(&KR[(size_t)((k0) + rkey) * 32 + rch * 8]); } while (0)
; __device__ __forceinline__ void finishSM(f32x16& p0, f32x16& p1, float alpha, float& l_reg, bf16x8& pa0, bf16x8& pa1, bf16x8& pa2, bf16x8& pa3) {
; #pragma unroll
;     for (int r = 0; r < 16; ++r) p1[r] = __builtin_amdgcn_exp2f(p1[r]);
;     float ps;
;     { typedef float f32x2 __attribute__((ext_vector_type(2))); f32x2 s0 = {p0[0], p0[1]}, s1 = {p1[0], p1[1]};
; #pragma unroll
;       for (int r = 2; r < 16; r += 2) { s0 += (f32x2){p0[r], p0[r + 1]}; s1 += (f32x2){p1[r], p1[r + 1]}; }
;       s0 += s1; ps = s0.x + s0.y; }
;     { auto rr = __builtin_amdgcn_permlane32_swap(__float_as_uint(ps), __float_as_uint(ps), false, false);
;       ps = __uint_as_float(rr[0]) + __uint_as_float(rr[1]); }
;     l_reg = l_reg * alpha + ps;
;     ...
;     PK4(p0, 0, pa0); PK4(p0, 8, pa1); PK4(p1, 0, pa2); PK4(p1, 8, pa3);
;     ...
; }
; __device__ __forceinline__ void qkt(f32x16& p0, f32x16& p1, const char* Ks, const bf16x8* qr, int r32, int hi) {
;     p0 = f32x16{}; p1 = f32x16{};
; #pragma unroll
;     for (int d0 = 0; d0 < 6; ++d0) { const int cb = (d0 * 16 + hi * 8) * 2;
;         bf16x8 b0 = *reinterpret_cast<const bf16x8*>(Ks + KSWZ(r32, cb));
;         bf16x8 b1 = *reinterpret_cast<const bf16x8*>(Ks + KSWZ(32 + r32, cb));
;         p0 = __builtin_amdgcn_mfma_f32_32x32x16_bf16(b0, qr[d0], p0, 0, 0, 0);
;         p1 = __builtin_amdgcn_mfma_f32_32x32x16_bf16(b1, qr[d0], p1, 0, 0, 0); }
; __device__ __forceinline__ void attn_body(const bf16_t* __restrict__ Qb, const bf16_t* __restrict__ KVh, const bf16_t* __restrict__ KR, const float* __restrict__ ropeq,
;                                           bf16_t* __restrict__ Ob, int seq, char* lds, const int tid) {
;     ...
;         SBAR(); qkt(pA0, pA1, K_lds + bc * SHM_K, qr, r32, hi);
;         finishSM(pB0, pB1, alB, l_reg, pa0, pa1, pa2, pa3); SBAR();
;         if (j + 3 < NT) SLOAD(SE, (j + 3) * KVBLK); SBAR();
;         pv_d0(o, vb0 + bp * (int)SHM_V, pa0, pa1, pa2, pa3); partialSM(pA0, pA1, m_reg, mnA, alA);
;         SWAIT(); SWRITE(bn, SO);
.Lattn_cb2:
	s_add_u32 s63, s14, s59
	v_add_u32_e32 v254, s15, v188
	ds_read_b128 v[114:117], v254 offset:49152
	ds_read_b128 v[118:121], v254 offset:57344
	v_add_f32_e32 v176, v232, v234
	v_add_f32_e32 v177, v233, v235
	v_cvt_pk_bf16_f32 v232, v232, v233
	v_cvt_pk_bf16_f32 v233, v234, v235
	v_add_f32_e32 v176, v236, v176
	v_add_f32_e32 v177, v237, v177
	v_cvt_pk_bf16_f32 v234, v236, v237
	v_add_f32_e32 v176, v238, v176
	v_add_f32_e32 v177, v239, v177
	v_cvt_pk_bf16_f32 v235, v238, v239
	v_add_f32_e32 v176, v240, v176
	v_add_f32_e32 v177, v241, v177
	v_cvt_pk_bf16_f32 v236, v240, v241
	v_add_f32_e32 v176, v242, v176
	v_add_f32_e32 v177, v243, v177
	v_cvt_pk_bf16_f32 v237, v242, v243
	v_add_u32_e32 v254, s15, v189
	ds_read_b128 v[248:251], v254 offset:49152
	ds_read_b128 v[240:243], v254 offset:57344
	v_add_f32_e32 v176, v244, v176
	v_add_f32_e32 v177, v245, v177
	v_cvt_pk_bf16_f32 v238, v244, v245
	s_waitcnt lgkmcnt(2)
	v_mfma_f32_32x32x16_bf16 v[48:63], v[114:117], v[78:81], 0
	v_add_f32_e32 v176, v246, v176
	v_add_f32_e32 v177, v247, v177
	v_cvt_pk_bf16_f32 v239, v246, v247
	v_exp_f32_e32 v122, v122
	v_exp_f32_e32 v123, v123
	v_mfma_f32_32x32x16_bf16 v[32:47], v[118:121], v[78:81], 0
	v_add_u32_e32 v254, s15, v212
	ds_read_b128 v[114:117], v254 offset:49152
	ds_read_b128 v[118:121], v254 offset:57344
	v_exp_f32_e32 v124, v124
	v_exp_f32_e32 v125, v125
	v_permlane32_swap_b32_e32 v232, v234
	v_permlane32_swap_b32_e32 v233, v235
	s_waitcnt lgkmcnt(2)
	v_mfma_f32_32x32x16_bf16 v[48:63], v[248:251], v[74:77], v[48:63]
	v_permlane32_swap_b32_e32 v236, v238
	v_permlane32_swap_b32_e32 v237, v239
	v_exp_f32_e32 v126, v126
	v_exp_f32_e32 v127, v127
	v_add_f32_e32 v244, v122, v124
	v_add_f32_e32 v245, v123, v125
	v_mfma_f32_32x32x16_bf16 v[32:47], v[240:243], v[74:77], v[32:47]
	v_add_u32_e32 v254, s15, v213
	ds_read_b128 v[248:251], v254 offset:49152
	ds_read_b128 v[240:243], v254 offset:57344
	v_exp_f32_e32 v128, v128
	v_exp_f32_e32 v129, v129
	v_add_f32_e32 v244, v126, v244
	v_add_f32_e32 v245, v127, v245
	v_exp_f32_e32 v178, v178
	v_exp_f32_e32 v179, v179
	s_waitcnt lgkmcnt(2)
	v_mfma_f32_32x32x16_bf16 v[48:63], v[114:117], v[70:73], v[48:63]
	v_add_f32_e32 v244, v128, v244
	v_add_f32_e32 v245, v129, v245
	v_exp_f32_e32 v202, v202
	v_exp_f32_e32 v203, v203
	v_add_f32_e32 v244, v178, v244
	v_add_f32_e32 v245, v179, v245
	v_exp_f32_e32 v228, v228
	s_waitcnt vmcnt(0)
	s_xor_b32 s58, s58, 0x400
	v_mov_b32_e32 v255, s58
	v_cndmask_b32_e64 v255, 0, v255, s[0:1]
	v_add3_u32 v254, s22, v217, v255
	v_add_u32_e32 v255, v254, v218
	v_add_u32_e32 v254, v254, v219
	ds_write_b128 v255, v[106:109]
	ds_write_b128 v254, v[110:113]
	s_cmp_eq_u64 s[2:3], 0
	s_cbranch_scc1 .Lattn_swA
	v_add_u32_e32 v254, s22, v186
	ds_write_b128 v254, v[102:105] offset:49152
.Lattn_swA:
	v_mfma_f32_32x32x16_bf16 v[32:47], v[118:121], v[70:73], v[32:47]
	v_add_u32_e32 v254, s15, v214
	ds_read_b128 v[114:117], v254 offset:49152
	ds_read_b128 v[118:121], v254 offset:57344
	v_exp_f32_e32 v229, v229
	v_add_f32_e32 v244, v202, v244
	v_add_f32_e32 v245, v203, v245
	v_exp_f32_e32 v230, v230
	v_exp_f32_e32 v231, v231
	v_add_f32_e32 v244, v228, v244
	v_add_f32_e32 v245, v229, v245
	s_cmp_gt_u32 s17, 60
	s_cbranch_scc1 .Lattn_slA
	v_lshl_add_u64 v[90:91], s[40:41], 0, v[168:169]
	global_load_dwordx4 v[90:93], v[90:91], off
	v_lshl_add_u64 v[94:95], s[42:43], 0, v[168:169]
	global_load_dwordx4 v[94:97], v[94:95], off
	v_lshl_add_u64 v[98:99], s[26:27], 0, v[170:171]
	global_load_dwordx4 v[98:101], v[98:99], off
.Lattn_slA:
	s_waitcnt lgkmcnt(4)
	v_mfma_f32_32x32x16_bf16 v[48:63], v[248:251], v[66:69], v[48:63]
	v_add_f32_e32 v244, v230, v244
	v_add_f32_e32 v245, v231, v245
	v_add_f32_e32 v176, v244, v176
	v_add_f32_e32 v177, v245, v177
	v_cvt_pk_bf16_f32 v122, v122, v123
	v_cvt_pk_bf16_f32 v123, v124, v125
	v_cvt_pk_bf16_f32 v124, v126, v127
	v_mfma_f32_32x32x16_bf16 v[32:47], v[240:243], v[66:69], v[32:47]
	v_add_u32_e32 v254, s15, v215
	ds_read_b128 v[248:251], v254 offset:49152
	ds_read_b128 v[240:243], v254 offset:57344
	v_cvt_pk_bf16_f32 v125, v128, v129
	v_cvt_pk_bf16_f32 v126, v178, v179
	v_cvt_pk_bf16_f32 v127, v202, v203
	v_cvt_pk_bf16_f32 v128, v228, v229
	v_cvt_pk_bf16_f32 v129, v230, v231
	s_waitcnt lgkmcnt(2)
	v_mfma_f32_32x32x16_bf16 v[48:63], v[114:117], v[82:85], v[48:63]
	v_add_f32_e32 v178, v176, v177
	v_mov_b32_e32 v228, v178
	v_permlane32_swap_b32_e32 v122, v124
	v_permlane32_swap_b32_e32 v123, v125
	v_mfma_f32_32x32x16_bf16 v[32:47], v[118:121], v[82:85], v[32:47]
	v_add_u32_e32 v246, s63, v185
	ds_read_b64_tr_b16 v[114:115], v246 offset:0
	ds_read_b64_tr_b16 v[116:117], v246 offset:2048
	ds_read_b64_tr_b16 v[118:119], v246 offset:4096
	ds_read_b64_tr_b16 v[120:121], v246 offset:6144
	v_permlane32_swap_b32_e32 v178, v228
	v_permlane32_swap_b32_e32 v126, v128
	v_permlane32_swap_b32_e32 v127, v129
	s_waitcnt lgkmcnt(4)
	v_mfma_f32_32x32x16_bf16 v[48:63], v[248:251], v[86:89], v[48:63]
	v_mfma_f32_32x32x16_bf16 v[32:47], v[240:243], v[86:89], v[32:47]
	ds_read_b64_tr_b16 v[248:249], v246 offset:8192
	ds_read_b64_tr_b16 v[250:251], v246 offset:10240
	ds_read_b64_tr_b16 v[240:241], v246 offset:12288
	ds_read_b64_tr_b16 v[242:243], v246 offset:14336
	s_waitcnt lgkmcnt(8)
	s_cmp_eq_u64 s[2:3], 0
	s_cbranch_scc0 .Lattn_cb3
	s_barrier
